# NA row-max via permlane32/16 swaps instead of two ds_bpermute, hot loops kept at their 8-byte placement phase
# baseline (speedup 1.0000x reference)
.LBB0_435:
	v_mov_b32_e32 v0, v115
	v_mov_b32_e32 v1, v115
	v_max_f32_e32 v2, v230, v230
	s_nop 0
	v_permlane32_swap_b32_e32 v1, v0
	v_max_f32_e32 v0, v0, v1
	v_mov_b32_e32 v1, v0
	s_nop 1
	v_permlane16_swap_b32_e32 v1, v0
	v_max_f32_e32 v0, v0, v1
	v_sub_f32_e32 v1, v0, v230
	v_cmp_ge_f32_e32 vcc, s56, v1
	s_cmp_eq_u64 vcc, exec
	v_max_f32_e32 v0, v2, v0
	s_cselect_b64 s[30:31], -1, 0
	s_cmp_lg_u64 vcc, exec
	v_cndmask_b32_e64 v115, v0, v230, s[30:31]
	s_cselect_b64 s[72:73], -1, 0
	s_andn2_b64 vcc, exec, s[66:67]
	s_mov_b64 s[66:67], -1
	s_cbranch_vccz .LBB0_441
	s_andn2_b64 vcc, exec, s[66:67]
	s_cbranch_vccz .LBB0_442

.LBB0_439:
	v_exp_f32_e32 v15, v15
	v_cndmask_b32_e64 v116, v114, 1.0, s[30:31]
	s_add_i32 s82, s82, 1
	v_cvt_pk_bf16_f32 v0, v0, v1
	v_add_f32_e32 v114, v15, v131
	v_fmac_f32_e32 v114, v229, v116
	v_cvt_pk_bf16_f32 v1, v2, v3
	v_cvt_pk_bf16_f32 v2, v4, v5
	v_cvt_pk_bf16_f32 v3, v6, v7
	v_cvt_pk_bf16_f32 v4, v8, v9
	v_cvt_pk_bf16_f32 v5, v10, v11
	v_cvt_pk_bf16_f32 v6, v12, v13
	v_cvt_pk_bf16_f32 v7, v14, v15
	ds_read_b64_tr_b16 v[10:11], v181 offset:21056
	ds_read_b64_tr_b16 v[8:9], v181 offset:16448
	ds_read_b64_tr_b16 v[14:15], v181 offset:21088
	ds_read_b64_tr_b16 v[12:13], v181 offset:16480
	ds_read_b64_tr_b16 v[118:119], v180 offset:21056
	ds_read_b64_tr_b16 v[116:117], v180 offset:16448
	ds_read_b64_tr_b16 v[122:123], v180 offset:21088
	ds_read_b64_tr_b16 v[120:121], v180 offset:16480
	s_waitcnt lgkmcnt(8)
	v_mfma_f32_16x16x32_bf16 v[46:49], v[102:105], v[0:3], v[46:49]
	v_mfma_f32_16x16x32_bf16 v[42:45], v[98:101], v[0:3], v[42:45]
	v_mfma_f32_16x16x32_bf16 v[46:49], v[110:113], v[4:7], v[46:49]
	v_mfma_f32_16x16x32_bf16 v[42:45], v[106:109], v[4:7], v[42:45]
	ds_read_b64_tr_b16 v[100:101], v181 offset:21120
	ds_read_b64_tr_b16 v[98:99], v181 offset:16512
	ds_read_b64_tr_b16 v[104:105], v181 offset:21152
	ds_read_b64_tr_b16 v[102:103], v181 offset:16544
	ds_read_b64_tr_b16 v[108:109], v180 offset:21120
	ds_read_b64_tr_b16 v[106:107], v180 offset:16512
	ds_read_b64_tr_b16 v[112:113], v180 offset:21152
	ds_read_b64_tr_b16 v[110:111], v180 offset:16544
	s_waitcnt lgkmcnt(14)
	v_mfma_f32_16x16x32_bf16 v[8:11], v[8:11], v[0:3], v[38:41]
	s_waitcnt lgkmcnt(10)
	v_mfma_f32_16x16x32_bf16 v[38:41], v[116:119], v[4:7], v[8:11]
	v_mfma_f32_16x16x32_bf16 v[8:11], v[12:15], v[0:3], v[34:37]
	s_waitcnt lgkmcnt(8)
	v_mfma_f32_16x16x32_bf16 v[34:37], v[120:123], v[4:7], v[8:11]
	s_nop 5
	ds_read_b64_tr_b16 v[10:11], v181 offset:21184
	ds_read_b64_tr_b16 v[8:9], v181 offset:16576
	ds_read_b64_tr_b16 v[14:15], v181 offset:21216
	ds_read_b64_tr_b16 v[12:13], v181 offset:16608
	ds_read_b64_tr_b16 v[118:119], v180 offset:21184
	ds_read_b64_tr_b16 v[116:117], v180 offset:16576
	ds_read_b64_tr_b16 v[122:123], v180 offset:21216
	ds_read_b64_tr_b16 v[120:121], v180 offset:16608
	s_waitcnt lgkmcnt(14)
	v_mfma_f32_16x16x32_bf16 v[30:33], v[98:101], v[0:3], v[30:33]
	v_add_u32_e32 v221, 0x7c, v221
	s_cmp_lg_u32 s82, 11
	s_waitcnt lgkmcnt(12)
	v_mfma_f32_16x16x32_bf16 v[26:29], v[102:105], v[0:3], v[26:29]
	s_waitcnt lgkmcnt(6)
	v_mfma_f32_16x16x32_bf16 v[8:11], v[8:11], v[0:3], v[22:25]
	s_waitcnt lgkmcnt(4)
	v_mfma_f32_16x16x32_bf16 v[0:3], v[12:15], v[0:3], v[18:21]
	v_mfma_f32_16x16x32_bf16 v[30:33], v[106:109], v[4:7], v[30:33]
	v_mfma_f32_16x16x32_bf16 v[26:29], v[110:113], v[4:7], v[26:29]
	s_waitcnt lgkmcnt(2)
	v_mfma_f32_16x16x32_bf16 v[22:25], v[116:119], v[4:7], v[8:11]
	s_waitcnt lgkmcnt(0)
	v_mfma_f32_16x16x32_bf16 v[18:21], v[120:123], v[4:7], v[0:3]
	s_cbranch_scc0 .LBB0_443
	v_mov_b32_e32 v229, v114
	v_mov_b32_e32 v230, v115
	s_branch .LBB0_391
